# latent attention: score-tile K reads pipelined one tile ahead, exp argument folded into one fma, ctx K/V block staging and ctx-attention task loads batched (each confirmed with attention phases repeat
# speedup vs baseline: 1.0047x; 1.0047x over previous
.LBB0_378:
	v_mov_b32_e32 v216, v128
	v_ashrrev_i32_e32 v216, 3, v216
	v_lshlrev_b32_e32 v220, 7, v216
	v_mov_b32_e32 v221, 0
	v_lshl_add_u64 v[220:221], v[0:1], 0, v[220:221]
	global_load_dwordx4 v[200:203], v[220:221], off
	v_mul_u32_u24_e32 v216, 0x90, v216
	v_add_u32_e32 v216, v216, v46
	v_add_u32_e32 v217, 0x200, v128
	v_ashrrev_i32_e32 v217, 3, v217
	v_lshlrev_b32_e32 v220, 7, v217
	v_mov_b32_e32 v221, 0
	v_lshl_add_u64 v[220:221], v[0:1], 0, v[220:221]
	global_load_dwordx4 v[204:207], v[220:221], off
	v_mul_u32_u24_e32 v217, 0x90, v217
	v_add_u32_e32 v217, v217, v46
	v_add_u32_e32 v218, 0x400, v128
	v_ashrrev_i32_e32 v218, 3, v218
	v_lshlrev_b32_e32 v220, 7, v218
	v_mov_b32_e32 v221, 0
	v_lshl_add_u64 v[220:221], v[0:1], 0, v[220:221]
	global_load_dwordx4 v[208:211], v[220:221], off
	v_mul_u32_u24_e32 v218, 0x90, v218
	v_add_u32_e32 v218, v218, v46
	v_add_u32_e32 v219, 0x600, v128
	v_ashrrev_i32_e32 v219, 3, v219
	v_lshlrev_b32_e32 v220, 7, v219
	v_mov_b32_e32 v221, 0
	v_lshl_add_u64 v[220:221], v[0:1], 0, v[220:221]
	global_load_dwordx4 v[212:215], v[220:221], off
	v_mul_u32_u24_e32 v219, 0x90, v219
	v_add_u32_e32 v219, v219, v46
	v_lshl_add_u64 v[0:1], v[48:49], 0, s[4:5]
	v_mov_b32_e32 v222, v128
	v_ashrrev_i32_e32 v222, 5, v222
	v_lshlrev_b32_e32 v220, 9, v222
	v_mov_b32_e32 v221, 0
	v_lshl_add_u64 v[220:221], v[0:1], 0, v[220:221]
	global_load_dwordx4 v[226:229], v[220:221], off
	v_mul_u32_u24_e32 v222, 0x210, v222
	v_add_u32_e32 v222, v222, v50
	v_add_u32_e32 v223, 0x200, v128
	v_ashrrev_i32_e32 v223, 5, v223
	v_lshlrev_b32_e32 v220, 9, v223
	v_mov_b32_e32 v221, 0
	v_lshl_add_u64 v[220:221], v[0:1], 0, v[220:221]
	global_load_dwordx4 v[230:233], v[220:221], off
	v_mul_u32_u24_e32 v223, 0x210, v223
	v_add_u32_e32 v223, v223, v50
	v_add_u32_e32 v224, 0x400, v128
	v_ashrrev_i32_e32 v224, 5, v224
	v_lshlrev_b32_e32 v220, 9, v224
	v_mov_b32_e32 v221, 0
	v_lshl_add_u64 v[220:221], v[0:1], 0, v[220:221]
	global_load_dwordx4 v[234:237], v[220:221], off
	v_mul_u32_u24_e32 v224, 0x210, v224
	v_add_u32_e32 v224, v224, v50
	v_add_u32_e32 v225, 0x600, v128
	v_ashrrev_i32_e32 v225, 5, v225
	v_lshlrev_b32_e32 v220, 9, v225
	v_mov_b32_e32 v221, 0
	v_lshl_add_u64 v[220:221], v[0:1], 0, v[220:221]
	global_load_dwordx4 v[238:241], v[220:221], off
	v_mul_u32_u24_e32 v225, 0x210, v225
	v_add_u32_e32 v225, v225, v50
	s_waitcnt vmcnt(7)
	ds_write_b128 v216, v[200:203]
	s_waitcnt vmcnt(6)
	ds_write_b128 v217, v[204:207]
	s_waitcnt vmcnt(5)
	ds_write_b128 v218, v[208:211]
	s_waitcnt vmcnt(4)
	ds_write_b128 v219, v[212:215]
	s_waitcnt vmcnt(3)
	ds_write_b128 v222, v[226:229] offset:36864
	s_waitcnt vmcnt(2)
	ds_write_b128 v223, v[230:233] offset:36864
	s_waitcnt vmcnt(1)
	ds_write_b128 v224, v[234:237] offset:36864
	s_waitcnt vmcnt(0)
	ds_write_b128 v225, v[238:241] offset:36864

.LBB0_388:
	v_mov_b32_e32 v247, 0xf149f2ca
	v_med3_i32 v4, s79, 4, 60
	v_lshlrev_b32_e32 v164, 6, v4
	v_or_b32_e32 v24, v164, v137
	s_add_i32 s16, s73, s79
	v_add_u32_e32 v148, 0xffffff00, v164
	v_ashrrev_i32_e32 v25, 31, v24
	v_readfirstlane_b32 s18, v4
	v_med3_i32 v5, s16, 4, 60
	v_add_u32_e32 v4, v148, v137
	v_add_u32_e32 v8, v55, v164
	v_add_u32_e32 v12, v140, v164
	v_add_u32_e32 v16, v141, v164
	v_lshlrev_b64 v[20:21], 12, v[24:25]
	v_or_b32_e32 v24, 64, v24
	v_add_u32_e32 v28, v142, v164
	v_add_u32_e32 v32, v143, v164
	v_readfirstlane_b32 s19, v5
	v_ashrrev_i32_e32 v5, 31, v4
	v_ashrrev_i32_e32 v9, 31, v8
	v_ashrrev_i32_e32 v13, 31, v12
	v_ashrrev_i32_e32 v17, 31, v16
	v_ashrrev_i32_e32 v25, 31, v24
	v_ashrrev_i32_e32 v29, 31, v28
	v_ashrrev_i32_e32 v33, 31, v32
	v_lshlrev_b64 v[4:5], 12, v[4:5]
	v_lshlrev_b64 v[8:9], 12, v[8:9]
	v_lshlrev_b64 v[12:13], 12, v[12:13]
	v_lshlrev_b64 v[16:17], 12, v[16:17]
	v_lshlrev_b64 v[24:25], 12, v[24:25]
	v_lshlrev_b64 v[28:29], 12, v[28:29]
	v_lshlrev_b64 v[32:33], 12, v[32:33]
	v_lshl_add_u64 v[4:5], v[78:79], 0, v[4:5]
	v_lshl_add_u64 v[8:9], v[78:79], 0, v[8:9]
	v_lshl_add_u64 v[12:13], v[78:79], 0, v[12:13]
	v_lshl_add_u64 v[16:17], v[78:79], 0, v[16:17]
	v_lshl_add_u64 v[20:21], v[78:79], 0, v[20:21]
	v_lshl_add_u64 v[24:25], v[78:79], 0, v[24:25]
	v_lshl_add_u64 v[28:29], v[78:79], 0, v[28:29]
	v_lshl_add_u64 v[32:33], v[78:79], 0, v[32:33]
	global_load_dwordx4 v[4:7], v[4:5], off offset:2048
	s_cmp_lt_u32 s79, 60
	global_load_dwordx4 v[8:11], v[8:9], off offset:2048
	s_cselect_b64 s[16:17], -1, 0
	global_load_dwordx4 v[12:15], v[12:13], off offset:2048
	s_cmp_gt_u32 s79, 59
	global_load_dwordx4 v[16:19], v[16:17], off offset:2048
	s_nop 0
	global_load_dwordx4 v[20:23], v[20:21], off offset:2048
	s_nop 0
	global_load_dwordx4 v[24:27], v[24:25], off offset:2048
	s_nop 0
	global_load_dwordx4 v[28:31], v[28:29], off offset:2048
	s_nop 0
	global_load_dwordx4 v[32:35], v[32:33], off offset:2048
	s_cbranch_scc1 .LBB0_390
	v_add_u32_e32 v0, v144, v164
	v_ashrrev_i32_e32 v1, 31, v0
	v_lshlrev_b64 v[0:1], 12, v[0:1]
	v_lshl_add_u64 v[0:1], v[78:79], 0, v[0:1]
	global_load_dwordx4 v[0:3], v[0:1], off offset:2048
.LBB0_390:
	s_barrier
	s_waitcnt vmcnt(7)
	ds_write_b128 v124, v[4:7]
	s_waitcnt vmcnt(6)
	ds_write_b128 v124, v[8:11] offset:8192
	s_waitcnt vmcnt(5)
	ds_write_b128 v124, v[12:15] offset:16384
	s_waitcnt vmcnt(4)
	ds_write_b128 v124, v[16:19] offset:24576
	s_waitcnt vmcnt(3)
	ds_write_b128 v124, v[20:23] offset:32768
	s_waitcnt vmcnt(2)
	ds_write_b128 v124, v[24:27] offset:40960
	s_waitcnt vmcnt(1)
	ds_write_b128 v124, v[28:31] offset:49152
	v_cndmask_b32_e64 v4, 0, 1, s[16:17]
	v_cmp_ne_u32_e64 s[40:41], 1, v4
	s_andn2_b64 vcc, exec, s[16:17]
	s_waitcnt vmcnt(0)
	ds_write_b128 v124, v[32:35] offset:57344
	s_cbranch_vccnz .LBB0_392
	ds_write_b128 v129, v[0:3]
.LBB0_392:
	s_mov_b32 s32, 0x3fb8aa3b
	v_add_u32_e32 v16, s6, v147
	v_med3_i32 v4, s80, 4, 60
	v_ashrrev_i32_e32 v17, 31, v16
	v_add_u32_e32 v22, s81, v4
	v_lshlrev_b64 v[4:5], 12, v[16:17]
	v_lshl_add_u64 v[4:5], v[56:57], 0, v[4:5]
	global_load_dwordx4 v[8:11], v[4:5], off
	s_nop 0
	global_load_dwordx4 v[4:7], v[4:5], off offset:64
	s_sub_i32 s18, s19, s18
	v_lshl_add_u32 v18, s18, 13, v146
	v_add_u32_e32 v26, v18, v138
	s_waitcnt lgkmcnt(0)
	s_barrier
	ds_read_b128 v[12:15], v26
	v_add_u32_e32 v27, v18, v139
	ds_read_b128 v[18:21], v27
	s_waitcnt vmcnt(1) lgkmcnt(1)
	v_mfma_f32_16x16x32_bf16 v[12:15], v[12:15], v[8:11], 0
	s_waitcnt vmcnt(0) lgkmcnt(0)
	v_mfma_f32_16x16x32_bf16 v[12:15], v[18:21], v[4:7], v[12:15]
	v_mul_lo_u32 v18, v22, 31
	v_ashrrev_i32_e32 v19, 31, v18
	v_lshlrev_b64 v[18:19], 2, v[18:19]
	v_lshl_add_u64 v[32:33], s[4:5], 0, v[18:19]
	v_lshl_add_u64 v[18:19], v[62:63], 2, v[32:33]
	v_lshl_add_u64 v[20:21], v[64:65], 2, v[32:33]
	v_lshl_add_u64 v[22:23], v[66:67], 2, v[32:33]
	v_lshl_add_u64 v[24:25], v[68:69], 2, v[32:33]
	global_load_dword v166, v[18:19], off offset:432
	global_load_dword v165, v[20:21], off offset:432
	global_load_dword v168, v[22:23], off offset:432
	global_load_dword v167, v[24:25], off offset:432
	global_load_dword v175, v[18:19], off offset:556
	global_load_dword v173, v[20:21], off offset:556
	global_load_dword v176, v[22:23], off offset:556
	global_load_dword v174, v[24:25], off offset:556
	global_load_dword v183, v[18:19], off offset:680
	global_load_dword v181, v[20:21], off offset:680
	global_load_dword v184, v[22:23], off offset:680
	global_load_dword v182, v[24:25], off offset:680
	global_load_dword v192, v[18:19], off offset:804
	global_load_dword v190, v[20:21], off offset:804
	global_load_dword v193, v[22:23], off offset:804
	global_load_dword v191, v[24:25], off offset:804
	global_load_dword v200, v[18:19], off offset:928
	global_load_dword v198, v[20:21], off offset:928
	global_load_dword v201, v[22:23], off offset:928
	global_load_dword v199, v[24:25], off offset:928
	global_load_dword v208, v[18:19], off offset:1052
	global_load_dword v206, v[20:21], off offset:1052
	global_load_dword v209, v[22:23], off offset:1052
	global_load_dword v207, v[24:25], off offset:1052
	global_load_dword v216, v[18:19], off offset:1176
	global_load_dword v214, v[20:21], off offset:1176
	global_load_dword v217, v[22:23], off offset:1176
	global_load_dword v215, v[24:25], off offset:1176
	global_load_dword v224, v[18:19], off offset:1300
	global_load_dword v222, v[20:21], off offset:1300
	global_load_dword v225, v[22:23], off offset:1300
	global_load_dword v223, v[24:25], off offset:1300
	s_waitcnt vmcnt(28)
	v_fmac_f32_e32 v166, 0x3e000000, v12
	v_cndmask_b32_e64 v166, v247, v166, s[28:29]
	v_fmac_f32_e32 v165, 0x3e000000, v13
	v_cndmask_b32_e64 v165, v247, v165, s[48:49]
	v_fmac_f32_e32 v168, 0x3e000000, v14
	v_cndmask_b32_e64 v168, v247, v168, s[24:25]
	v_fmac_f32_e32 v167, 0x3e000000, v15
	v_cndmask_b32_e64 v167, v247, v167, s[96:97]
	ds_read_b128 v[12:15], v26 offset:512
	ds_read_b128 v[26:29], v27 offset:512
	s_waitcnt lgkmcnt(1)
	v_mfma_f32_16x16x32_bf16 v[12:15], v[12:15], v[8:11], 0
	s_waitcnt lgkmcnt(0)
	v_mfma_f32_16x16x32_bf16 v[12:15], v[26:29], v[4:7], v[12:15]
	v_lshl_add_u64 v[26:27], v[70:71], 2, v[32:33]
	v_lshl_add_u64 v[28:29], v[72:73], 2, v[32:33]
	v_lshl_add_u64 v[30:31], v[74:75], 2, v[32:33]
	v_lshl_add_u64 v[32:33], v[76:77], 2, v[32:33]
	global_load_dword v171, v[26:27], off offset:432
	global_load_dword v169, v[28:29], off offset:432
	global_load_dword v172, v[30:31], off offset:432
	global_load_dword v170, v[32:33], off offset:432
	global_load_dword v179, v[26:27], off offset:556
	global_load_dword v177, v[28:29], off offset:556
	global_load_dword v180, v[30:31], off offset:556
	global_load_dword v178, v[32:33], off offset:556
	global_load_dword v187, v[26:27], off offset:680
	global_load_dword v185, v[28:29], off offset:680
	global_load_dword v189, v[30:31], off offset:680
	global_load_dword v186, v[32:33], off offset:680
	global_load_dword v196, v[26:27], off offset:804
	global_load_dword v194, v[28:29], off offset:804
	global_load_dword v197, v[30:31], off offset:804
	global_load_dword v195, v[32:33], off offset:804
	global_load_dword v204, v[26:27], off offset:928
	global_load_dword v202, v[28:29], off offset:928
	global_load_dword v205, v[30:31], off offset:928
	global_load_dword v203, v[32:33], off offset:928
	global_load_dword v212, v[26:27], off offset:1052
	global_load_dword v210, v[28:29], off offset:1052
	global_load_dword v213, v[30:31], off offset:1052
	global_load_dword v211, v[32:33], off offset:1052
	global_load_dword v220, v[26:27], off offset:1176
	global_load_dword v218, v[28:29], off offset:1176
	global_load_dword v221, v[30:31], off offset:1176
	global_load_dword v219, v[32:33], off offset:1176
	global_load_dword v228, v[26:27], off offset:1300
	global_load_dword v226, v[28:29], off offset:1300
	global_load_dword v229, v[30:31], off offset:1300
	global_load_dword v227, v[32:33], off offset:1300
	s_waitcnt vmcnt(28)
	v_fmac_f32_e32 v171, 0x3e000000, v12
	v_cndmask_b32_e64 v171, v247, v171, s[26:27]
	v_fmac_f32_e32 v169, 0x3e000000, v13
	v_cndmask_b32_e64 v169, v247, v169, s[2:3]
	v_fmac_f32_e32 v172, 0x3e000000, v14
	v_cndmask_b32_e64 v172, v247, v172, s[64:65]
	v_fmac_f32_e32 v170, 0x3e000000, v15
	v_cndmask_b32_e64 v170, v247, v170, s[0:1]
	s_add_i32 s19, s18, 1
	v_lshl_add_u32 v35, s19, 13, v146
	v_add_u32_e32 v34, v35, v138
	ds_read_b128 v[152:155], v34
	v_add_u32_e32 v35, v35, v139
	ds_read_b128 v[80:83], v35
	ds_read_b128 v[156:159], v34 offset:512
	ds_read_b128 v[160:163], v35 offset:512
	s_waitcnt lgkmcnt(3)
	v_mfma_f32_16x16x32_bf16 v[12:15], v[152:155], v[8:11], 0
	s_waitcnt lgkmcnt(2)
	v_mfma_f32_16x16x32_bf16 v[12:15], v[80:83], v[4:7], v[12:15]
	s_waitcnt vmcnt(56)
	s_nop 6
	v_fmac_f32_e32 v175, 0x3e000000, v12
	v_cndmask_b32_e64 v175, v247, v175, s[28:29]
	v_fmac_f32_e32 v173, 0x3e000000, v13
	v_cndmask_b32_e64 v173, v247, v173, s[48:49]
	v_fmac_f32_e32 v176, 0x3e000000, v14
	v_cndmask_b32_e64 v176, v247, v176, s[24:25]
	v_fmac_f32_e32 v174, 0x3e000000, v15
	v_cndmask_b32_e64 v174, v247, v174, s[96:97]
	s_add_i32 s20, s18, 2
	v_lshl_add_u32 v35, s20, 13, v146
	v_add_u32_e32 v34, v35, v138
	ds_read_b128 v[152:155], v34
	v_add_u32_e32 v35, v35, v139
	ds_read_b128 v[80:83], v35
	s_waitcnt lgkmcnt(3)
	v_mfma_f32_16x16x32_bf16 v[12:15], v[156:159], v[8:11], 0
	s_waitcnt lgkmcnt(2)
	v_mfma_f32_16x16x32_bf16 v[12:15], v[160:163], v[4:7], v[12:15]
	s_waitcnt vmcnt(24)
	s_nop 6
	v_fmac_f32_e32 v179, 0x3e000000, v12
	v_cndmask_b32_e64 v179, v247, v179, s[26:27]
	v_fmac_f32_e32 v177, 0x3e000000, v13
	v_cndmask_b32_e64 v177, v247, v177, s[2:3]
	v_fmac_f32_e32 v180, 0x3e000000, v14
	v_cndmask_b32_e64 v180, v247, v180, s[64:65]
	v_fmac_f32_e32 v178, 0x3e000000, v15
	v_cndmask_b32_e64 v178, v247, v178, s[0:1]
	ds_read_b128 v[156:159], v34 offset:512
	ds_read_b128 v[160:163], v35 offset:512
	s_waitcnt lgkmcnt(3)
	v_mfma_f32_16x16x32_bf16 v[12:15], v[152:155], v[8:11], 0
	s_waitcnt lgkmcnt(2)
	v_mfma_f32_16x16x32_bf16 v[12:15], v[80:83], v[4:7], v[12:15]
	s_waitcnt vmcnt(52)
	s_nop 6
	v_fmac_f32_e32 v183, 0x3e000000, v12
	v_cndmask_b32_e64 v183, v247, v183, s[28:29]
	v_fmac_f32_e32 v181, 0x3e000000, v13
	v_cndmask_b32_e64 v181, v247, v181, s[48:49]
	v_fmac_f32_e32 v184, 0x3e000000, v14
	v_cndmask_b32_e64 v184, v247, v184, s[24:25]
	v_fmac_f32_e32 v182, 0x3e000000, v15
	v_cndmask_b32_e64 v182, v247, v182, s[96:97]
	s_add_i32 s21, s18, 3
	v_lshl_add_u32 v35, s21, 13, v146
	v_add_u32_e32 v34, v35, v138
	ds_read_b128 v[152:155], v34
	v_add_u32_e32 v35, v35, v139
	ds_read_b128 v[80:83], v35
	s_waitcnt lgkmcnt(3)
	v_mfma_f32_16x16x32_bf16 v[12:15], v[156:159], v[8:11], 0
	s_waitcnt lgkmcnt(2)
	v_mfma_f32_16x16x32_bf16 v[12:15], v[160:163], v[4:7], v[12:15]
	s_waitcnt vmcnt(20)
	s_nop 6
	v_fmac_f32_e32 v187, 0x3e000000, v12
	v_cndmask_b32_e64 v187, v247, v187, s[26:27]
	v_fmac_f32_e32 v185, 0x3e000000, v13
	v_cndmask_b32_e64 v185, v247, v185, s[2:3]
	v_fmac_f32_e32 v189, 0x3e000000, v14
	v_cndmask_b32_e64 v189, v247, v189, s[64:65]
	v_fmac_f32_e32 v186, 0x3e000000, v15
	v_cndmask_b32_e64 v186, v247, v186, s[0:1]
	ds_read_b128 v[156:159], v34 offset:512
	ds_read_b128 v[160:163], v35 offset:512
	s_waitcnt lgkmcnt(3)
	v_mfma_f32_16x16x32_bf16 v[12:15], v[152:155], v[8:11], 0
	s_waitcnt lgkmcnt(2)
	v_mfma_f32_16x16x32_bf16 v[12:15], v[80:83], v[4:7], v[12:15]
	s_waitcnt vmcnt(48)
	s_nop 6
	v_fmac_f32_e32 v192, 0x3e000000, v12
	v_cndmask_b32_e64 v192, v247, v192, s[28:29]
	v_fmac_f32_e32 v190, 0x3e000000, v13
	v_cndmask_b32_e64 v190, v247, v190, s[48:49]
	v_fmac_f32_e32 v193, 0x3e000000, v14
	v_cndmask_b32_e64 v193, v247, v193, s[24:25]
	v_fmac_f32_e32 v191, 0x3e000000, v15
	v_cndmask_b32_e64 v191, v247, v191, s[96:97]
	s_add_i32 s30, s18, 4
	v_lshl_add_u32 v35, s30, 13, v146
	v_add_u32_e32 v34, v35, v138
	ds_read_b128 v[152:155], v34
	v_add_u32_e32 v35, v35, v139
	ds_read_b128 v[80:83], v35
	s_waitcnt lgkmcnt(3)
	v_mfma_f32_16x16x32_bf16 v[12:15], v[156:159], v[8:11], 0
	s_waitcnt lgkmcnt(2)
	v_mfma_f32_16x16x32_bf16 v[12:15], v[160:163], v[4:7], v[12:15]
	s_waitcnt vmcnt(16)
	s_nop 6
	v_fmac_f32_e32 v196, 0x3e000000, v12
	v_cndmask_b32_e64 v196, v247, v196, s[26:27]
	v_fmac_f32_e32 v194, 0x3e000000, v13
	v_cndmask_b32_e64 v194, v247, v194, s[2:3]
	v_fmac_f32_e32 v197, 0x3e000000, v14
	v_cndmask_b32_e64 v197, v247, v197, s[64:65]
	v_fmac_f32_e32 v195, 0x3e000000, v15
	v_cndmask_b32_e64 v195, v247, v195, s[0:1]
	ds_read_b128 v[156:159], v34 offset:512
	ds_read_b128 v[160:163], v35 offset:512
	s_waitcnt lgkmcnt(3)
	v_mfma_f32_16x16x32_bf16 v[12:15], v[152:155], v[8:11], 0
	s_waitcnt lgkmcnt(2)
	v_mfma_f32_16x16x32_bf16 v[12:15], v[80:83], v[4:7], v[12:15]
	s_waitcnt vmcnt(44)
	s_nop 6
	v_fmac_f32_e32 v200, 0x3e000000, v12
	v_cndmask_b32_e64 v200, v247, v200, s[28:29]
	v_fmac_f32_e32 v198, 0x3e000000, v13
	v_cndmask_b32_e64 v198, v247, v198, s[48:49]
	v_fmac_f32_e32 v201, 0x3e000000, v14
	v_cndmask_b32_e64 v201, v247, v201, s[24:25]
	v_fmac_f32_e32 v199, 0x3e000000, v15
	v_cndmask_b32_e64 v199, v247, v199, s[96:97]
	s_add_i32 s31, s18, 5
	v_lshl_add_u32 v35, s31, 13, v146
	v_add_u32_e32 v34, v35, v138
	ds_read_b128 v[152:155], v34
	v_add_u32_e32 v35, v35, v139
	ds_read_b128 v[80:83], v35
	s_waitcnt lgkmcnt(3)
	v_mfma_f32_16x16x32_bf16 v[12:15], v[156:159], v[8:11], 0
	s_waitcnt lgkmcnt(2)
	v_mfma_f32_16x16x32_bf16 v[12:15], v[160:163], v[4:7], v[12:15]
	s_waitcnt vmcnt(12)
	s_nop 6
	v_fmac_f32_e32 v204, 0x3e000000, v12
	v_cndmask_b32_e64 v204, v247, v204, s[26:27]
	v_fmac_f32_e32 v202, 0x3e000000, v13
	v_cndmask_b32_e64 v202, v247, v202, s[2:3]
	v_fmac_f32_e32 v205, 0x3e000000, v14
	v_cndmask_b32_e64 v205, v247, v205, s[64:65]
	v_fmac_f32_e32 v203, 0x3e000000, v15
	v_cndmask_b32_e64 v203, v247, v203, s[0:1]
	ds_read_b128 v[156:159], v34 offset:512
	ds_read_b128 v[160:163], v35 offset:512
	s_waitcnt lgkmcnt(3)
	v_mfma_f32_16x16x32_bf16 v[12:15], v[152:155], v[8:11], 0
	s_waitcnt lgkmcnt(2)
	v_mfma_f32_16x16x32_bf16 v[12:15], v[80:83], v[4:7], v[12:15]
	s_waitcnt vmcnt(40)
	s_nop 6
	v_fmac_f32_e32 v208, 0x3e000000, v12
	v_cndmask_b32_e64 v208, v247, v208, s[28:29]
	v_fmac_f32_e32 v206, 0x3e000000, v13
	v_cndmask_b32_e64 v206, v247, v206, s[48:49]
	v_fmac_f32_e32 v209, 0x3e000000, v14
	v_cndmask_b32_e64 v209, v247, v209, s[24:25]
	v_fmac_f32_e32 v207, 0x3e000000, v15
	v_cndmask_b32_e64 v207, v247, v207, s[96:97]
	s_add_i32 s33, s18, 6
	v_lshl_add_u32 v35, s33, 13, v146
	v_add_u32_e32 v34, v35, v138
	ds_read_b128 v[152:155], v34
	v_add_u32_e32 v35, v35, v139
	ds_read_b128 v[80:83], v35
	s_waitcnt lgkmcnt(3)
	v_mfma_f32_16x16x32_bf16 v[12:15], v[156:159], v[8:11], 0
	s_waitcnt lgkmcnt(2)
	v_mfma_f32_16x16x32_bf16 v[12:15], v[160:163], v[4:7], v[12:15]
	s_waitcnt vmcnt(8)
	s_nop 6
	v_fmac_f32_e32 v212, 0x3e000000, v12
	v_cndmask_b32_e64 v212, v247, v212, s[26:27]
	v_fmac_f32_e32 v210, 0x3e000000, v13
	v_cndmask_b32_e64 v210, v247, v210, s[2:3]
	v_fmac_f32_e32 v213, 0x3e000000, v14
	v_cndmask_b32_e64 v213, v247, v213, s[64:65]
	v_fmac_f32_e32 v211, 0x3e000000, v15
	v_cndmask_b32_e64 v211, v247, v211, s[0:1]
	ds_read_b128 v[156:159], v34 offset:512
	ds_read_b128 v[160:163], v35 offset:512
	s_waitcnt lgkmcnt(3)
	v_mfma_f32_16x16x32_bf16 v[12:15], v[152:155], v[8:11], 0
	s_waitcnt lgkmcnt(2)
	v_mfma_f32_16x16x32_bf16 v[12:15], v[80:83], v[4:7], v[12:15]
	s_waitcnt vmcnt(36)
	s_nop 6
	v_fmac_f32_e32 v216, 0x3e000000, v12
	v_cndmask_b32_e64 v216, v247, v216, s[28:29]
	v_fmac_f32_e32 v214, 0x3e000000, v13
	v_cndmask_b32_e64 v214, v247, v214, s[48:49]
	v_fmac_f32_e32 v217, 0x3e000000, v14
	v_cndmask_b32_e64 v217, v247, v217, s[24:25]
	v_fmac_f32_e32 v215, 0x3e000000, v15
	v_cndmask_b32_e64 v215, v247, v215, s[96:97]
	s_add_i32 s34, s18, 7
	v_lshl_add_u32 v35, s34, 13, v146
	v_add_u32_e32 v34, v35, v138
	ds_read_b128 v[152:155], v34
	v_add_u32_e32 v35, v35, v139
	ds_read_b128 v[80:83], v35
	s_waitcnt lgkmcnt(3)
	v_mfma_f32_16x16x32_bf16 v[12:15], v[156:159], v[8:11], 0
	s_waitcnt lgkmcnt(2)
	v_mfma_f32_16x16x32_bf16 v[12:15], v[160:163], v[4:7], v[12:15]
	s_waitcnt vmcnt(4)
	s_nop 6
	v_fmac_f32_e32 v220, 0x3e000000, v12
	v_cndmask_b32_e64 v220, v247, v220, s[26:27]
	v_fmac_f32_e32 v218, 0x3e000000, v13
	v_cndmask_b32_e64 v218, v247, v218, s[2:3]
	v_fmac_f32_e32 v221, 0x3e000000, v14
	v_cndmask_b32_e64 v221, v247, v221, s[64:65]
	v_fmac_f32_e32 v219, 0x3e000000, v15
	v_cndmask_b32_e64 v219, v247, v219, s[0:1]
	ds_read_b128 v[156:159], v34 offset:512
	ds_read_b128 v[160:163], v35 offset:512
	s_waitcnt lgkmcnt(3)
	v_mfma_f32_16x16x32_bf16 v[12:15], v[152:155], v[8:11], 0
	s_waitcnt lgkmcnt(2)
	v_mfma_f32_16x16x32_bf16 v[12:15], v[80:83], v[4:7], v[12:15]
	s_waitcnt vmcnt(32)
	s_nop 6
	v_fmac_f32_e32 v224, 0x3e000000, v12
	v_cndmask_b32_e64 v224, v247, v224, s[28:29]
	v_fmac_f32_e32 v222, 0x3e000000, v13
	v_cndmask_b32_e64 v222, v247, v222, s[48:49]
	v_fmac_f32_e32 v225, 0x3e000000, v14
	v_cndmask_b32_e64 v225, v247, v225, s[24:25]
	v_fmac_f32_e32 v223, 0x3e000000, v15
	v_cndmask_b32_e64 v223, v247, v223, s[96:97]
	s_waitcnt lgkmcnt(1)
	v_mfma_f32_16x16x32_bf16 v[12:15], v[156:159], v[8:11], 0
	s_waitcnt lgkmcnt(0)
	v_mfma_f32_16x16x32_bf16 v[12:15], v[160:163], v[4:7], v[12:15]
	s_waitcnt vmcnt(0)
	s_nop 6
	v_fmac_f32_e32 v228, 0x3e000000, v12
	v_cndmask_b32_e64 v228, v247, v228, s[26:27]
	v_fmac_f32_e32 v226, 0x3e000000, v13
	v_cndmask_b32_e64 v226, v247, v226, s[2:3]
	v_fmac_f32_e32 v229, 0x3e000000, v14
	v_cndmask_b32_e64 v229, v247, v229, s[64:65]
	v_fmac_f32_e32 v227, 0x3e000000, v15
	v_cndmask_b32_e64 v227, v247, v227, s[0:1]
	v_max_f32_e32 v12, v167, v167
	v_max_f32_e32 v13, v168, v168
	v_max_f32_e32 v12, v13, v12
	v_max_f32_e32 v13, v170, v170
	v_max_f32_e32 v14, v172, v172
	v_max_f32_e32 v13, v14, v13
	v_max3_f32 v12, v166, v165, v12
	v_max3_f32 v13, v171, v169, v13
	v_max3_f32 v12, v12, s69, v13
	v_max_f32_e32 v13, v174, v174
	v_max_f32_e32 v14, v176, v176
	v_max_f32_e32 v13, v14, v13
	v_max_f32_e32 v14, v178, v178
	v_max_f32_e32 v15, v180, v180
	v_max_f32_e32 v14, v15, v14
	v_max3_f32 v13, v175, v173, v13
	v_max3_f32 v14, v179, v177, v14
	v_max3_f32 v12, v12, v13, v14
	v_max_f32_e32 v13, v182, v182
	v_max_f32_e32 v14, v184, v184
	v_max_f32_e32 v13, v14, v13
	v_max_f32_e32 v14, v186, v186
	v_max_f32_e32 v15, v189, v189
	v_max_f32_e32 v14, v15, v14
	v_max3_f32 v13, v183, v181, v13
	v_max3_f32 v14, v187, v185, v14
	v_max3_f32 v12, v12, v13, v14
	v_max_f32_e32 v13, v191, v191
	v_max_f32_e32 v14, v193, v193
	v_max_f32_e32 v13, v14, v13
	v_max_f32_e32 v14, v195, v195
	v_max_f32_e32 v15, v197, v197
	v_max_f32_e32 v14, v15, v14
	v_max3_f32 v13, v192, v190, v13
	v_max3_f32 v14, v196, v194, v14
	v_max3_f32 v12, v12, v13, v14
	v_max_f32_e32 v13, v199, v199
	v_max_f32_e32 v14, v201, v201
	v_max_f32_e32 v13, v14, v13
	v_max_f32_e32 v14, v203, v203
	v_max_f32_e32 v15, v205, v205
	v_max_f32_e32 v14, v15, v14
	v_max3_f32 v13, v200, v198, v13
	v_max3_f32 v14, v204, v202, v14
	v_max3_f32 v12, v12, v13, v14
	v_max_f32_e32 v13, v207, v207
	v_max_f32_e32 v14, v209, v209
	v_max_f32_e32 v13, v14, v13
	v_max_f32_e32 v14, v211, v211
	v_max_f32_e32 v15, v213, v213
	v_max_f32_e32 v14, v15, v14
	v_max3_f32 v13, v208, v206, v13
	v_max3_f32 v14, v212, v210, v14
	v_max3_f32 v12, v12, v13, v14
	v_max_f32_e32 v13, v215, v215
	v_max_f32_e32 v14, v217, v217
	v_max_f32_e32 v13, v14, v13
	v_max_f32_e32 v14, v219, v219
	v_max_f32_e32 v15, v221, v221
	v_max_f32_e32 v14, v15, v14
	v_max3_f32 v13, v216, v214, v13
	v_max3_f32 v14, v220, v218, v14
	v_max3_f32 v12, v12, v13, v14
	v_max_f32_e32 v13, v223, v223
	v_max_f32_e32 v14, v225, v225
	v_max_f32_e32 v13, v14, v13
	v_max_f32_e32 v14, v227, v227
	v_max_f32_e32 v15, v229, v229
	v_max_f32_e32 v14, v15, v14
	v_max3_f32 v13, v224, v222, v13
	v_max3_f32 v14, v228, v226, v14
	v_max3_f32 v28, v12, v13, v14
	ds_read_b128 v[12:15], v134
	ds_read_b128 v[18:21], v134 offset:64
	s_waitcnt lgkmcnt(1)
	v_mfma_f32_16x16x32_bf16 v[12:15], v[12:15], v[8:11], 0
	s_and_b64 vcc, exec, s[40:41]
	s_waitcnt lgkmcnt(0)
	v_mfma_f32_16x16x32_bf16 v[18:21], v[18:21], v[4:7], v[12:15]
	s_nop 7
	v_pk_mul_f32 v[12:13], v[20:21], s[12:13] op_sel_hi:[1,0]
	ds_read_b128 v[20:23], v134 offset:576
	ds_read_b128 v[24:27], v134 offset:640
	s_waitcnt lgkmcnt(1)
	v_mfma_f32_16x16x32_bf16 v[20:23], v[20:23], v[8:11], 0
	v_mul_f32_e64 v18, v18, s12
	v_mul_f32_e64 v19, v19, s12
	v_max_f32_e32 v14, v12, v13
	v_max3_f32 v29, v18, v19, v14
	s_waitcnt lgkmcnt(0)
	v_mfma_f32_16x16x32_bf16 v[20:23], v[24:27], v[4:7], v[20:23]
	s_nop 7
	v_pk_mul_f32 v[14:15], v[22:23], s[12:13] op_sel_hi:[1,0]
	v_pk_mul_f32 v[22:23], v[20:21], s[12:13] op_sel_hi:[1,0]
	v_max_f32_e32 v20, v14, v15
	v_max3_f32 v20, v22, v23, v20
	v_max3_f32 v80, v28, v29, v20
	ds_read_b128 v[24:27], v134 offset:4608
	ds_read_b128 v[28:31], v134 offset:4672
	s_waitcnt lgkmcnt(1)
	v_mfma_f32_16x16x32_bf16 v[24:27], v[24:27], v[8:11], 0
	s_waitcnt lgkmcnt(0)
	v_mfma_f32_16x16x32_bf16 v[24:27], v[28:31], v[4:7], v[24:27]
	ds_read_b128 v[28:31], v134 offset:5184
	ds_read_b128 v[32:35], v134 offset:5248
	s_waitcnt lgkmcnt(1)
	v_mfma_f32_16x16x32_bf16 v[28:31], v[28:31], v[8:11], 0
	s_nop 3
	v_mul_f32_e64 v20, v26, s12
	v_mul_f32_e64 v21, v27, s12
	v_pk_mul_f32 v[26:27], v[24:25], s[12:13] op_sel_hi:[1,0]
	v_max_f32_e32 v24, v20, v21
	s_waitcnt lgkmcnt(0)
	v_mfma_f32_16x16x32_bf16 v[28:31], v[32:35], v[4:7], v[28:31]
	v_max3_f32 v81, v26, v27, v24
	s_nop 6
	v_pk_mul_f32 v[24:25], v[30:31], s[12:13] op_sel_hi:[1,0]
	v_pk_mul_f32 v[30:31], v[28:29], s[12:13] op_sel_hi:[1,0]
	v_max_f32_e32 v28, v24, v25
	v_max3_f32 v28, v30, v31, v28
	v_max3_f32 v88, v80, v81, v28
	ds_read_b128 v[32:35], v134 offset:9216
	ds_read_b128 v[80:83], v134 offset:9280
	s_waitcnt lgkmcnt(1)
	v_mfma_f32_16x16x32_bf16 v[32:35], v[32:35], v[8:11], 0
	s_waitcnt lgkmcnt(0)
	v_mfma_f32_16x16x32_bf16 v[32:35], v[80:83], v[4:7], v[32:35]
	ds_read_b128 v[80:83], v134 offset:9792
	ds_read_b128 v[84:87], v134 offset:9856
	s_waitcnt lgkmcnt(1)
	v_mfma_f32_16x16x32_bf16 v[80:83], v[80:83], v[8:11], 0
	s_nop 3
	v_mul_f32_e64 v28, v34, s12
	v_mul_f32_e64 v29, v35, s12
	v_pk_mul_f32 v[34:35], v[32:33], s[12:13] op_sel_hi:[1,0]
	v_max_f32_e32 v32, v28, v29
	s_waitcnt lgkmcnt(0)
	v_mfma_f32_16x16x32_bf16 v[80:83], v[84:87], v[4:7], v[80:83]
	v_max3_f32 v89, v34, v35, v32
	s_nop 6
	v_pk_mul_f32 v[32:33], v[82:83], s[12:13] op_sel_hi:[1,0]
	v_pk_mul_f32 v[82:83], v[80:81], s[12:13] op_sel_hi:[1,0]
	v_max_f32_e32 v80, v32, v33
	v_max3_f32 v80, v82, v83, v80
	v_max3_f32 v96, v88, v89, v80
	ds_read_b128 v[84:87], v134 offset:13824
	ds_read_b128 v[88:91], v134 offset:13888
	s_waitcnt lgkmcnt(1)
	v_mfma_f32_16x16x32_bf16 v[84:87], v[84:87], v[8:11], 0
	s_waitcnt lgkmcnt(0)
	v_mfma_f32_16x16x32_bf16 v[84:87], v[88:91], v[4:7], v[84:87]
	ds_read_b128 v[88:91], v134 offset:14400
	ds_read_b128 v[92:95], v134 offset:14464
	s_waitcnt lgkmcnt(1)
	v_mfma_f32_16x16x32_bf16 v[88:91], v[88:91], v[8:11], 0
	s_nop 3
	v_mul_f32_e64 v80, v86, s12
	v_mul_f32_e64 v81, v87, s12
	v_pk_mul_f32 v[86:87], v[84:85], s[12:13] op_sel_hi:[1,0]
	v_max_f32_e32 v84, v80, v81
	s_waitcnt lgkmcnt(0)
	v_mfma_f32_16x16x32_bf16 v[88:91], v[92:95], v[4:7], v[88:91]
	v_max3_f32 v97, v86, v87, v84
	s_nop 6
	v_pk_mul_f32 v[84:85], v[90:91], s[12:13] op_sel_hi:[1,0]
	v_pk_mul_f32 v[90:91], v[88:89], s[12:13] op_sel_hi:[1,0]
	v_max_f32_e32 v88, v84, v85
	v_max3_f32 v88, v90, v91, v88
	v_max3_f32 v104, v96, v97, v88
	ds_read_b128 v[92:95], v134 offset:18432
	ds_read_b128 v[96:99], v134 offset:18496
	s_waitcnt lgkmcnt(1)
	v_mfma_f32_16x16x32_bf16 v[92:95], v[92:95], v[8:11], 0
	s_waitcnt lgkmcnt(0)
	v_mfma_f32_16x16x32_bf16 v[92:95], v[96:99], v[4:7], v[92:95]
	ds_read_b128 v[96:99], v134 offset:19008
	ds_read_b128 v[100:103], v134 offset:19072
	s_waitcnt lgkmcnt(1)
	v_mfma_f32_16x16x32_bf16 v[96:99], v[96:99], v[8:11], 0
	s_nop 3
	v_mul_f32_e64 v88, v94, s12
	v_mul_f32_e64 v89, v95, s12
	v_pk_mul_f32 v[94:95], v[92:93], s[12:13] op_sel_hi:[1,0]
	v_max_f32_e32 v92, v88, v89
	s_waitcnt lgkmcnt(0)
	v_mfma_f32_16x16x32_bf16 v[96:99], v[100:103], v[4:7], v[96:99]
	v_max3_f32 v105, v94, v95, v92
	s_nop 6
	v_pk_mul_f32 v[92:93], v[98:99], s[12:13] op_sel_hi:[1,0]
	v_pk_mul_f32 v[98:99], v[96:97], s[12:13] op_sel_hi:[1,0]
	v_max_f32_e32 v96, v92, v93
	v_max3_f32 v96, v98, v99, v96
	v_max3_f32 v112, v104, v105, v96
	ds_read_b128 v[100:103], v134 offset:23040
	ds_read_b128 v[104:107], v134 offset:23104
	s_waitcnt lgkmcnt(1)
	v_mfma_f32_16x16x32_bf16 v[100:103], v[100:103], v[8:11], 0
	s_waitcnt lgkmcnt(0)
	v_mfma_f32_16x16x32_bf16 v[100:103], v[104:107], v[4:7], v[100:103]
	ds_read_b128 v[104:107], v134 offset:23616
	ds_read_b128 v[108:111], v134 offset:23680
	s_waitcnt lgkmcnt(1)
	v_mfma_f32_16x16x32_bf16 v[104:107], v[104:107], v[8:11], 0
	s_nop 3
	v_mul_f32_e64 v96, v102, s12
	v_mul_f32_e64 v97, v103, s12
	v_pk_mul_f32 v[102:103], v[100:101], s[12:13] op_sel_hi:[1,0]
	v_max_f32_e32 v100, v96, v97
	s_waitcnt lgkmcnt(0)
	v_mfma_f32_16x16x32_bf16 v[104:107], v[108:111], v[4:7], v[104:107]
	v_max3_f32 v113, v102, v103, v100
	s_nop 6
	v_pk_mul_f32 v[100:101], v[106:107], s[12:13] op_sel_hi:[1,0]
	v_pk_mul_f32 v[104:105], v[104:105], s[12:13] op_sel_hi:[1,0]
	v_max_f32_e32 v106, v100, v101
	v_max3_f32 v106, v104, v105, v106
	v_max3_f32 v230, v112, v113, v106
	ds_read_b128 v[106:109], v134 offset:27648
	ds_read_b128 v[110:113], v134 offset:27712
	s_waitcnt lgkmcnt(1)
	v_mfma_f32_16x16x32_bf16 v[106:109], v[106:109], v[8:11], 0
	s_waitcnt lgkmcnt(0)
	v_mfma_f32_16x16x32_bf16 v[108:111], v[110:113], v[4:7], v[106:109]
	s_nop 7
	v_pk_mul_f32 v[106:107], v[110:111], s[12:13] op_sel_hi:[1,0]
	v_pk_mul_f32 v[108:109], v[108:109], s[12:13] op_sel_hi:[1,0]
	v_max_f32_e32 v110, v106, v107
	v_max3_f32 v231, v108, v109, v110
	ds_read_b128 v[110:113], v134 offset:28224
	ds_read_b128 v[114:117], v134 offset:28288
	s_waitcnt lgkmcnt(1)
	v_mfma_f32_16x16x32_bf16 v[110:113], v[110:113], v[8:11], 0
	s_waitcnt lgkmcnt(0)
	v_mfma_f32_16x16x32_bf16 v[112:115], v[114:117], v[4:7], v[110:113]
	s_nop 7
	v_pk_mul_f32 v[110:111], v[114:115], s[12:13] op_sel_hi:[1,0]
	v_pk_mul_f32 v[112:113], v[112:113], s[12:13] op_sel_hi:[1,0]
	v_max_f32_e32 v114, v110, v111
	v_max3_f32 v114, v112, v113, v114
	v_max3_f32 v238, v230, v231, v114
	ds_read_b128 v[114:117], v134 offset:32256
	ds_read_b128 v[230:233], v134 offset:32320
	s_waitcnt lgkmcnt(1)
	v_mfma_f32_16x16x32_bf16 v[114:117], v[114:117], v[8:11], 0
	s_waitcnt lgkmcnt(0)
	v_mfma_f32_16x16x32_bf16 v[230:233], v[230:233], v[4:7], v[114:117]
	s_nop 7
	v_pk_mul_f32 v[114:115], v[232:233], s[12:13] op_sel_hi:[1,0]
	v_pk_mul_f32 v[116:117], v[230:231], s[12:13] op_sel_hi:[1,0]
	v_max_f32_e32 v230, v114, v115
	v_max3_f32 v239, v116, v117, v230
	ds_read_b128 v[230:233], v134 offset:32832
	ds_read_b128 v[234:237], v134 offset:32896
	s_waitcnt lgkmcnt(1)
	v_mfma_f32_16x16x32_bf16 v[8:11], v[230:233], v[8:11], 0
	s_waitcnt lgkmcnt(0)
	s_barrier
	v_mfma_f32_16x16x32_bf16 v[6:9], v[234:237], v[4:7], v[8:11]
	s_nop 7
	v_pk_mul_f32 v[4:5], v[8:9], s[12:13] op_sel_hi:[1,0]
	v_pk_mul_f32 v[6:7], v[6:7], s[12:13] op_sel_hi:[1,0]
	v_max_f32_e32 v8, v4, v5
	v_max3_f32 v8, v6, v7, v8
	v_max3_f32 v8, v238, v239, v8
	ds_bpermute_b32 v9, v131, v8
	s_waitcnt lgkmcnt(0)
	v_max_f32_e32 v9, v9, v9
	v_max_f32_e32 v8, v8, v9
	ds_bpermute_b32 v9, v132, v8
	s_waitcnt lgkmcnt(0)
	v_max_f32_e32 v9, v9, v9
	v_max_f32_e32 v8, v8, v9
	v_mul_f32_e32 v162, 0xbfb8aa3b, v8
	v_fma_f32 v10, v165, s32, v162
	v_exp_f32_e32 v165, v10
	v_fma_f32 v10, v168, s32, v162
	v_exp_f32_e32 v168, v10
	v_fma_f32 v10, v167, s32, v162
	v_exp_f32_e32 v167, v10
	v_fma_f32 v10, v171, s32, v162
	v_exp_f32_e32 v171, v10
	v_fma_f32 v10, v169, s32, v162
	v_exp_f32_e32 v230, v10
	v_fma_f32 v10, v172, s32, v162
	v_exp_f32_e32 v172, v10
	v_fma_f32 v10, v170, s32, v162
	v_exp_f32_e32 v231, v10
	v_fma_f32 v10, v175, s32, v162
	v_exp_f32_e32 v169, v10
	v_fma_f32 v10, v173, s32, v162
	v_exp_f32_e32 v170, v10
	v_fma_f32 v10, v176, s32, v162
	v_exp_f32_e32 v173, v10
	v_fma_f32 v10, v174, s32, v162
	v_exp_f32_e32 v174, v10
	v_fma_f32 v10, v179, s32, v162
	v_exp_f32_e32 v175, v10
	v_fma_f32 v10, v177, s32, v162
	v_exp_f32_e32 v177, v10
	v_fma_f32 v10, v180, s32, v162
	v_exp_f32_e32 v179, v10
	v_fma_f32 v10, v178, s32, v162
	v_exp_f32_e32 v232, v10
	v_fma_f32 v10, v183, s32, v162
	v_exp_f32_e32 v176, v10
	v_fma_f32 v10, v181, s32, v162
	v_exp_f32_e32 v178, v10
	v_fma_f32 v10, v184, s32, v162
	v_exp_f32_e32 v180, v10
	v_fma_f32 v10, v182, s32, v162
	v_exp_f32_e32 v181, v10
	v_fma_f32 v10, v187, s32, v162
	v_exp_f32_e32 v182, v10
	v_fma_f32 v10, v185, s32, v162
	v_exp_f32_e32 v184, v10
	v_fma_f32 v10, v189, s32, v162
	v_exp_f32_e32 v187, v10
	v_fma_f32 v10, v186, s32, v162
	v_exp_f32_e32 v189, v10
	v_fma_f32 v10, v192, s32, v162
	v_exp_f32_e32 v183, v10
	v_fma_f32 v10, v190, s32, v162
	v_exp_f32_e32 v185, v10
	v_fma_f32 v10, v193, s32, v162
	v_exp_f32_e32 v186, v10
	v_fma_f32 v10, v191, s32, v162
	v_exp_f32_e32 v190, v10
	v_fma_f32 v10, v196, s32, v162
	v_exp_f32_e32 v191, v10
	v_fma_f32 v10, v194, s32, v162
	v_exp_f32_e32 v193, v10
	v_fma_f32 v10, v197, s32, v162
	v_exp_f32_e32 v196, v10
	v_fma_f32 v10, v195, s32, v162
	v_exp_f32_e32 v197, v10
	v_fma_f32 v10, v200, s32, v162
	v_exp_f32_e32 v192, v10
	v_fma_f32 v10, v198, s32, v162
	v_exp_f32_e32 v194, v10
	v_fma_f32 v10, v201, s32, v162
	v_exp_f32_e32 v195, v10
	v_fma_f32 v10, v199, s32, v162
	v_exp_f32_e32 v198, v10
	v_fma_f32 v10, v204, s32, v162
	v_exp_f32_e32 v199, v10
	v_fma_f32 v10, v202, s32, v162
	v_exp_f32_e32 v201, v10
	v_fma_f32 v10, v205, s32, v162
	v_exp_f32_e32 v204, v10
	v_fma_f32 v10, v203, s32, v162
	v_exp_f32_e32 v205, v10
	v_fma_f32 v10, v208, s32, v162
	v_exp_f32_e32 v200, v10
	v_fma_f32 v10, v206, s32, v162
	v_exp_f32_e32 v202, v10
	v_fma_f32 v10, v209, s32, v162
	v_exp_f32_e32 v203, v10
	v_fma_f32 v10, v207, s32, v162
	v_exp_f32_e32 v206, v10
	v_fma_f32 v10, v212, s32, v162
	v_exp_f32_e32 v207, v10
	v_fma_f32 v10, v210, s32, v162
	v_exp_f32_e32 v209, v10
	v_fma_f32 v10, v213, s32, v162
	v_exp_f32_e32 v212, v10
	v_fma_f32 v10, v211, s32, v162
	v_exp_f32_e32 v233, v10
	v_fma_f32 v10, v216, s32, v162
	v_exp_f32_e32 v208, v10
	v_fma_f32 v10, v214, s32, v162
	v_exp_f32_e32 v210, v10
	v_fma_f32 v10, v217, s32, v162
	v_exp_f32_e32 v211, v10
	v_fma_f32 v10, v215, s32, v162
	v_exp_f32_e32 v214, v10
	v_fma_f32 v10, v220, s32, v162
	v_exp_f32_e32 v215, v10
	v_fma_f32 v10, v218, s32, v162
	v_exp_f32_e32 v217, v10
	v_fma_f32 v10, v221, s32, v162
	v_exp_f32_e32 v220, v10
	v_fma_f32 v10, v219, s32, v162
	v_exp_f32_e32 v234, v10
	v_fma_f32 v10, v224, s32, v162
	v_exp_f32_e32 v213, v10
	v_fma_f32 v10, v222, s32, v162
	v_exp_f32_e32 v216, v10
	v_fma_f32 v10, v225, s32, v162
	v_exp_f32_e32 v218, v10
	v_fma_f32 v10, v223, s32, v162
	v_exp_f32_e32 v221, v10
	v_fma_f32 v10, v228, s32, v162
	v_exp_f32_e32 v222, v10
	v_fma_f32 v10, v226, s32, v162
	v_fma_f32 v9, v166, s32, v162
	v_exp_f32_e32 v224, v10
	v_fma_f32 v10, v229, s32, v162
	v_exp_f32_e32 v166, v9
	v_exp_f32_e32 v226, v10
	v_fma_f32 v10, v227, s32, v162
	v_exp_f32_e32 v229, v10
	v_fma_f32 v10, v18, s32, v162
	v_add_f32_e32 v9, 0, v166
	v_add_f32_e32 v9, v165, v9
	v_exp_f32_e32 v219, v10
	v_fma_f32 v10, v19, s32, v162
	v_add_f32_e32 v9, v168, v9
	v_add_f32_e32 v9, v167, v9
	v_exp_f32_e32 v223, v10
	v_fma_f32 v10, v12, s32, v162
	v_add_f32_e32 v9, v171, v9
	v_add_f32_e32 v9, v230, v9
	v_exp_f32_e32 v225, v10
	v_fma_f32 v10, v13, s32, v162
	v_add_f32_e32 v9, v172, v9
	v_add_f32_e32 v9, v231, v9
	v_exp_f32_e32 v227, v10
	v_fma_f32 v10, v22, s32, v162
	v_add_f32_e32 v9, v169, v9
	v_add_f32_e32 v9, v170, v9
	v_exp_f32_e32 v228, v10
	v_fma_f32 v10, v23, s32, v162
	v_add_f32_e32 v9, v173, v9
	v_add_f32_e32 v9, v174, v9
	v_exp_f32_e32 v235, v10
	v_fma_f32 v10, v14, s32, v162
	v_add_f32_e32 v9, v175, v9
	v_add_f32_e32 v9, v177, v9
	v_exp_f32_e32 v236, v10
	v_fma_f32 v10, v15, s32, v162
	v_add_f32_e32 v9, v179, v9
	v_add_f32_e32 v9, v232, v9
	v_exp_f32_e32 v237, v10
	v_fma_f32 v10, v26, s32, v162
	v_add_f32_e32 v9, v176, v9
	v_add_f32_e32 v9, v178, v9
	v_exp_f32_e32 v22, v10
	v_fma_f32 v10, v27, s32, v162
	v_add_f32_e32 v9, v180, v9
	v_add_f32_e32 v9, v181, v9
	v_exp_f32_e32 v23, v10
	v_fma_f32 v10, v20, s32, v162
	v_add_f32_e32 v9, v182, v9
	v_add_f32_e32 v9, v184, v9
	v_exp_f32_e32 v20, v10
	v_fma_f32 v10, v21, s32, v162
	v_add_f32_e32 v9, v187, v9
	v_add_f32_e32 v9, v189, v9
	v_exp_f32_e32 v26, v10
	v_fma_f32 v10, v30, s32, v162
	v_add_f32_e32 v9, v183, v9
	v_add_f32_e32 v9, v185, v9
	v_exp_f32_e32 v27, v10
	v_fma_f32 v10, v31, s32, v162
	v_add_f32_e32 v9, v186, v9
	v_add_f32_e32 v9, v190, v9
	v_exp_f32_e32 v30, v10
	v_fma_f32 v10, v24, s32, v162
	v_add_f32_e32 v9, v191, v9
	v_add_f32_e32 v9, v193, v9
	v_exp_f32_e32 v31, v10
	v_fma_f32 v10, v25, s32, v162
	v_add_f32_e32 v9, v196, v9
	v_add_f32_e32 v9, v197, v9
	v_exp_f32_e32 v238, v10
	v_fma_f32 v10, v34, s32, v162
	v_add_f32_e32 v9, v192, v9
	v_add_f32_e32 v9, v194, v9
	v_exp_f32_e32 v21, v10
	v_fma_f32 v10, v35, s32, v162
	v_add_f32_e32 v9, v195, v9
	v_add_f32_e32 v9, v198, v9
	v_exp_f32_e32 v24, v10
	v_fma_f32 v10, v28, s32, v162
	v_add_f32_e32 v9, v199, v9
	v_add_f32_e32 v9, v201, v9
	v_exp_f32_e32 v25, v10
	v_fma_f32 v10, v29, s32, v162
	v_add_f32_e32 v9, v204, v9
	v_add_f32_e32 v9, v205, v9
	v_exp_f32_e32 v28, v10
	v_fma_f32 v10, v82, s32, v162
	v_add_f32_e32 v9, v200, v9
	v_add_f32_e32 v9, v202, v9
	v_exp_f32_e32 v34, v10
	v_fma_f32 v10, v83, s32, v162
	v_add_f32_e32 v9, v203, v9
	v_add_f32_e32 v9, v206, v9
	v_exp_f32_e32 v35, v10
	v_fma_f32 v10, v32, s32, v162
	v_add_f32_e32 v9, v207, v9
	v_add_f32_e32 v9, v209, v9
	v_exp_f32_e32 v82, v10
	v_fma_f32 v10, v33, s32, v162
	v_add_f32_e32 v9, v212, v9
	v_add_f32_e32 v9, v233, v9
	v_exp_f32_e32 v83, v10
	v_fma_f32 v10, v86, s32, v162
	v_add_f32_e32 v9, v208, v9
	v_add_f32_e32 v9, v210, v9
	v_exp_f32_e32 v29, v10
	v_fma_f32 v10, v87, s32, v162
	v_add_f32_e32 v9, v211, v9
	v_add_f32_e32 v9, v214, v9
	v_exp_f32_e32 v32, v10
	v_fma_f32 v10, v80, s32, v162
	v_add_f32_e32 v9, v215, v9
	v_add_f32_e32 v9, v217, v9
	v_exp_f32_e32 v33, v10
	v_fma_f32 v10, v81, s32, v162
	v_add_f32_e32 v9, v220, v9
	v_add_f32_e32 v9, v234, v9
	v_exp_f32_e32 v80, v10
	v_fma_f32 v10, v90, s32, v162
	v_add_f32_e32 v9, v213, v9
	v_add_f32_e32 v9, v216, v9
	v_exp_f32_e32 v86, v10
	v_fma_f32 v10, v91, s32, v162
	v_add_f32_e32 v9, v218, v9
	v_add_f32_e32 v9, v221, v9
	v_exp_f32_e32 v87, v10
	v_fma_f32 v10, v84, s32, v162
	v_add_f32_e32 v9, v222, v9
	v_add_f32_e32 v9, v224, v9
	v_exp_f32_e32 v91, v10
	v_fma_f32 v10, v85, s32, v162
	v_add_f32_e32 v9, v226, v9
	v_add_f32_e32 v9, v229, v9
	v_exp_f32_e32 v239, v10
	v_fma_f32 v10, v94, s32, v162
	v_add_f32_e32 v9, v219, v9
	v_add_f32_e32 v9, v223, v9
	v_exp_f32_e32 v81, v10
	v_fma_f32 v10, v95, s32, v162
	v_add_f32_e32 v9, v225, v9
	v_add_f32_e32 v9, v227, v9
	v_exp_f32_e32 v84, v10
	v_fma_f32 v10, v88, s32, v162
	v_add_f32_e32 v9, v228, v9
	v_add_f32_e32 v9, v235, v9
	v_exp_f32_e32 v90, v10
	v_fma_f32 v10, v89, s32, v162
	v_add_f32_e32 v9, v236, v9
	v_add_f32_e32 v9, v237, v9
	v_exp_f32_e32 v89, v10
	v_fma_f32 v10, v98, s32, v162
	v_add_f32_e32 v9, v22, v9
	v_add_f32_e32 v9, v23, v9
	v_exp_f32_e32 v94, v10
	v_fma_f32 v10, v99, s32, v162
	v_add_f32_e32 v9, v20, v9
	v_add_f32_e32 v9, v26, v9
	v_exp_f32_e32 v98, v10
	v_fma_f32 v10, v92, s32, v162
	v_add_f32_e32 v9, v27, v9
	v_add_f32_e32 v9, v30, v9
	v_exp_f32_e32 v240, v10
	v_fma_f32 v10, v93, s32, v162
	v_add_f32_e32 v9, v31, v9
	v_add_f32_e32 v9, v238, v9
	v_exp_f32_e32 v242, v10
	v_fma_f32 v10, v102, s32, v162
	v_add_f32_e32 v9, v21, v9
	v_add_f32_e32 v9, v24, v9
	v_exp_f32_e32 v92, v10
	v_fma_f32 v10, v103, s32, v162
	v_add_f32_e32 v9, v25, v9
	v_add_f32_e32 v9, v28, v9
	v_exp_f32_e32 v93, v10
	v_fma_f32 v10, v96, s32, v162
	v_add_f32_e32 v9, v34, v9
	v_add_f32_e32 v9, v35, v9
	v_exp_f32_e32 v102, v10
	v_fma_f32 v10, v97, s32, v162
	v_add_f32_e32 v9, v82, v9
	v_add_f32_e32 v9, v83, v9
	v_exp_f32_e32 v241, v10
	v_fma_f32 v10, v104, s32, v162
	v_add_f32_e32 v9, v29, v9
	v_add_f32_e32 v9, v32, v9
	v_exp_f32_e32 v243, v10
	v_fma_f32 v10, v105, s32, v162
	v_add_f32_e32 v9, v33, v9
	v_add_f32_e32 v9, v80, v9
	v_exp_f32_e32 v244, v10
	v_fma_f32 v10, v100, s32, v162
	v_add_f32_e32 v9, v86, v9
	v_add_f32_e32 v9, v87, v9
	v_exp_f32_e32 v245, v10
	v_fma_f32 v10, v101, s32, v162
	v_add_f32_e32 v9, v91, v9
	v_add_f32_e32 v9, v239, v9
	v_exp_f32_e32 v246, v10
	v_fma_f32 v10, v108, s32, v162
	v_add_f32_e32 v9, v81, v9
	v_add_f32_e32 v9, v84, v9
	v_exp_f32_e32 v105, v10
	v_fma_f32 v10, v109, s32, v162
	v_add_f32_e32 v9, v90, v9
	v_add_f32_e32 v9, v89, v9
	v_exp_f32_e32 v108, v10
	v_fma_f32 v10, v106, s32, v162
	v_add_f32_e32 v9, v94, v9
	v_add_f32_e32 v9, v98, v9
	v_exp_f32_e32 v106, v10
	v_fma_f32 v10, v107, s32, v162
	v_add_f32_e32 v9, v240, v9
	v_add_f32_e32 v9, v242, v9
	v_exp_f32_e32 v107, v10
	v_fma_f32 v10, v112, s32, v162
	v_add_f32_e32 v9, v92, v9
	v_add_f32_e32 v9, v93, v9
	v_exp_f32_e32 v109, v10
	v_fma_f32 v10, v113, s32, v162
	v_add_f32_e32 v9, v102, v9
	v_add_f32_e32 v9, v241, v9
	v_exp_f32_e32 v112, v10
	v_fma_f32 v10, v110, s32, v162
	v_add_f32_e32 v9, v243, v9
	v_add_f32_e32 v9, v244, v9
	v_exp_f32_e32 v110, v10
	v_fma_f32 v10, v111, s32, v162
	v_add_f32_e32 v9, v245, v9
	v_add_f32_e32 v9, v246, v9
	v_exp_f32_e32 v111, v10
	v_fma_f32 v10, v116, s32, v162
	v_add_f32_e32 v9, v105, v9
	v_add_f32_e32 v9, v108, v9
	v_exp_f32_e32 v95, v10
	v_fma_f32 v10, v117, s32, v162
	v_add_f32_e32 v9, v106, v9
	v_add_f32_e32 v9, v107, v9
	v_exp_f32_e32 v97, v10
	v_fma_f32 v10, v114, s32, v162
	v_add_f32_e32 v9, v109, v9
	v_add_f32_e32 v9, v112, v9
	v_exp_f32_e32 v96, v10
	v_fma_f32 v10, v115, s32, v162
	v_add_f32_e32 v9, v110, v9
	v_fma_f32 v6, v6, s32, v162
	v_add_f32_e32 v9, v111, v9
	v_exp_f32_e32 v99, v10
	v_fma_f32 v7, v7, s32, v162
	v_add_f32_e32 v9, v95, v9
	v_exp_f32_e32 v100, v6
	v_fma_f32 v4, v4, s32, v162
	v_add_f32_e32 v9, v97, v9
	v_exp_f32_e32 v101, v7
	v_fma_f32 v5, v5, s32, v162
	v_add_f32_e32 v9, v96, v9
	v_exp_f32_e32 v103, v4
	v_add_f32_e32 v9, v99, v9
	v_exp_f32_e32 v104, v5
	v_add_f32_e32 v6, v100, v9
	v_add_f32_e32 v6, v101, v6
	v_add_f32_e32 v4, v103, v6
	v_add_f32_e32 v4, v104, v4
	ds_bpermute_b32 v5, v131, v4
	s_waitcnt lgkmcnt(0)
	v_add_f32_e32 v85, v4, v5
	v_lshl_add_u64 v[4:5], v[148:149], 1, v[58:59]
	v_lshlrev_b32_e32 v148, 1, v164
	v_lshl_add_u64 v[18:19], v[58:59], 0, v[148:149]
	global_load_dwordx4 v[4:7], v[4:5], off
	s_nop 0
	global_load_dwordx4 v[8:11], v[18:19], off offset:-384
	global_load_dwordx4 v[12:15], v[18:19], off offset:-256
	global_load_dwordx4 v[114:117], v[18:19], off offset:-128
	global_load_dwordx4 v[248:251], v[18:19], off
	s_waitcnt vmcnt(4)
	ds_write_b128 v136, v[4:7]
	s_waitcnt vmcnt(3)
	ds_write_b128 v136, v[8:11] offset:128
	s_waitcnt vmcnt(2)
	ds_write_b128 v136, v[12:15] offset:256
	s_waitcnt vmcnt(1)
	ds_write_b128 v136, v[114:117] offset:384
	s_waitcnt vmcnt(0)
	ds_write_b128 v136, v[248:251] offset:512
	global_load_dwordx4 v[4:7], v[18:19], off offset:128
	global_load_dwordx4 v[8:11], v[18:19], off offset:256
	global_load_dwordx4 v[12:15], v[18:19], off offset:384
	ds_bpermute_b32 v88, v132, v85
	s_cbranch_vccnz .LBB0_387
	global_load_dwordx4 v[114:117], v[18:19], off offset:512
	s_waitcnt vmcnt(0)
	ds_write_b128 v136, v[114:117] offset:1024
	s_branch .LBB0_387
